# cross-half wait kept only where it is a real dependency (half 0 after phase 4); half 1 and phase 8 no longer poll
# speedup vs baseline: 1.0302x; 1.0005x over previous
.LBB0_151:
	s_cmp_lg_u32 s54, 4
	s_cbranch_scc1 .Lxw_done
	v_readlane_b32 s100, v255, 61
	s_nop 0
	s_cmp_lg_u32 s100, 0
	s_cbranch_scc1 .Lxw_done
